# v51: v41 + role-specific counted vmcnt waits in the P3 prompt scan (compute waves wait only for the ring slot they consume, exact counts 47..44, first iteration keeps the original waits)
# speedup vs baseline: 1.0109x; 1.0109x over previous
.LBB0_1203:
	s_min_u32 s16, s39, 57
	s_add_i32 s40, s16, 6
	s_mul_i32 s16, s40, 0x38000
	s_waitcnt lgkmcnt(0)
	s_barrier
	s_cmp_lg_u32 s39, 0
	s_cselect_b64 vcc, s[6:7], 0
	s_cbranch_vccnz .Lp3rx_a1
	s_waitcnt vmcnt(15)
	ds_write_b128 v99, v[2:5]
	s_waitcnt vmcnt(14)
	ds_write_b128 v119, v[10:13] offset:8704
	s_waitcnt vmcnt(13)
	ds_write_b128 v120, v[6:9] offset:18944
	s_waitcnt vmcnt(11)
	ds_write_b128 v121, v[22:25] offset:19456
	s_branch .Lp3rj_a1
.Lp3rx_a1:
	s_waitcnt vmcnt(47)
	ds_write_b128 v99, v[2:5]
	s_waitcnt vmcnt(46)
	ds_write_b128 v119, v[10:13] offset:8704
	s_waitcnt vmcnt(45)
	ds_write_b128 v120, v[6:9] offset:18944
	s_waitcnt vmcnt(44)
	ds_write_b128 v121, v[22:25] offset:19456
.Lp3rj_a1:
	v_lshl_add_u64 v[2:3], v[102:103], 0, s[16:17]
	v_lshl_add_u64 v[6:7], v[104:105], 0, s[16:17]
	s_lshl_b32 s40, s40, 12
	s_mov_b32 s41, s17
	global_load_dwordx4 v[2:5], v[2:3], off
	s_nop 0
	global_load_dwordx4 v[10:13], v[6:7], off
	v_lshl_add_u64 v[6:7], v[108:109], 0, s[40:41]
	v_lshl_add_u64 v[22:23], v[106:107], 0, s[16:17]
	global_load_dwordx4 v[6:9], v[6:7], off
	s_nop 0
	s_mov_b64 exec, s[100:101]
	global_load_dwordx4 v[22:25], v[22:23], off
	s_mov_b64 exec, -1
	s_and_b64 vcc, exec, s[2:3]
	v_add_u32_e32 v128, 0x6800, v123
	v_add_u32_e32 v101, 0x7800, v123
	s_cbranch_vccnz .LBB0_1205
	s_setprio 2
	v_add_u32_e32 v160, 0x6800, v123
	v_add_u32_e32 v161, 0x7800, v123
	ds_read2_b64 v[128:131], v160 offset0:192 offset1:196
	ds_read2_b64 v[132:135], v161 offset0:224 offset1:228
	ds_read2_b64 v[136:139], v160 offset0:200 offset1:204
	ds_read2_b64 v[140:143], v161 offset0:232 offset1:236
	ds_read2_b64 v[144:147], v160 offset0:208 offset1:212
	ds_read2_b64 v[148:151], v161 offset0:240 offset1:244
	ds_read2_b64 v[152:155], v160 offset0:216 offset1:220
	ds_read2_b64 v[156:159], v161 offset0:248 offset1:252
	ds_read_u16 v184, v124 offset:47616
	ds_read_u16 v185, v124 offset:47888
	ds_read_u16 v186, v124 offset:48160
	ds_read_u16 v179, v124 offset:48432
	ds_read_u16 v252, v124 offset:48704
	ds_read_u16 v253, v124 offset:48976
	v_cvt_pk_bf16_f32 v162, v70, v71
	v_cvt_pk_bf16_f32 v163, v72, v73
	v_cvt_pk_bf16_f32 v164, v66, v67
	v_cvt_pk_bf16_f32 v165, v68, v69
	s_waitcnt lgkmcnt(13)
	s_nop 0
	v_mfma_f32_16x16x32_bf16 v[170:173], v[128:131], v[162:165], 0
	s_waitcnt lgkmcnt(12)
	v_mfma_f32_16x16x32_bf16 v[174:177], v[132:135], v[162:165], 0
	ds_read_u16 v208, v124 offset:49248
	ds_read_u16 v209, v124 offset:49520
	ds_read_b128 v[180:183], v125 offset:36864
	v_cvt_pk_bf16_f32 v166, v74, v75
	v_cvt_pk_bf16_f32 v167, v76, v77
	v_cvt_pk_bf16_f32 v168, v78, v79
	v_cvt_pk_bf16_f32 v169, v80, v81
	s_waitcnt lgkmcnt(14)
	s_nop 0
	v_mfma_f32_16x16x32_bf16 v[170:173], v[136:139], v[166:169], v[170:173]
	s_waitcnt lgkmcnt(13)
	v_mfma_f32_16x16x32_bf16 v[174:177], v[140:143], v[166:169], v[174:177]
	ds_read_b128 v[188:191], v122 offset:47104
	ds_read_b128 v[192:195], v125 offset:38144
	v_cvt_pk_bf16_f32 v162, v62, v63
	v_cvt_pk_bf16_f32 v163, v64, v65
	v_cvt_pk_bf16_f32 v164, v54, v55
	v_cvt_pk_bf16_f32 v165, v56, v57
	s_waitcnt lgkmcnt(14)
	s_nop 0
	v_mfma_f32_16x16x32_bf16 v[170:173], v[144:147], v[162:165], v[170:173]
	s_waitcnt lgkmcnt(13)
	v_mfma_f32_16x16x32_bf16 v[174:177], v[148:151], v[162:165], v[174:177]
	ds_read_b128 v[232:235], v122 offset:47168
	ds_read_b128 v[236:239], v125 offset:39424
	v_cvt_pk_bf16_f32 v166, v42, v43
	v_cvt_pk_bf16_f32 v167, v44, v45
	v_cvt_pk_bf16_f32 v168, v58, v59
	v_cvt_pk_bf16_f32 v169, v60, v61
	s_waitcnt lgkmcnt(14)
	s_nop 0
	v_mfma_f32_16x16x32_bf16 v[170:173], v[152:155], v[166:169], v[170:173]
	s_waitcnt lgkmcnt(13)
	v_mfma_f32_16x16x32_bf16 v[174:177], v[156:159], v[166:169], v[174:177]
	ds_read_b128 v[240:243], v122 offset:47232
	ds_read_b128 v[244:247], v126 offset:36864
	s_waitcnt lgkmcnt(7)
	v_lshl_or_b32 v248, v185, 16, v184
	v_lshl_or_b32 v249, v179, 16, v186
	v_lshl_or_b32 v250, v253, 16, v252
	v_lshl_or_b32 v251, v209, 16, v208
	ds_read_b128 v[128:131], v122 offset:47296
	ds_read_b128 v[132:135], v125 offset:41984
	s_waitcnt lgkmcnt(7)
	v_pk_mul_f32 v[72:73], v[72:73], v[190:191]
	v_pk_mul_f32 v[70:71], v[70:71], v[188:189]
	ds_read_b128 v[136:139], v122 offset:47360
	ds_read_b128 v[140:143], v125 offset:43264
	v_mfma_f32_16x16x32_bf16 v[70:73], v[180:183], v[248:251], v[70:73]
	s_waitcnt lgkmcnt(7)
	v_pk_mul_f32 v[68:69], v[68:69], v[234:235]
	v_pk_mul_f32 v[66:67], v[66:67], v[232:233]
	ds_read_b128 v[144:147], v122 offset:47424
	ds_read_b128 v[148:151], v125 offset:44544
	v_mfma_f32_16x16x32_bf16 v[66:69], v[192:195], v[248:251], v[66:69]
	s_waitcnt lgkmcnt(7)
	v_pk_mul_f32 v[76:77], v[76:77], v[242:243]
	v_pk_mul_f32 v[74:75], v[74:75], v[240:241]
	ds_read_b128 v[152:155], v122 offset:47488
	ds_read_b128 v[156:159], v127 offset:36864
	v_mfma_f32_16x16x32_bf16 v[74:77], v[236:239], v[248:251], v[74:77]
	s_waitcnt lgkmcnt(7)
	v_pk_mul_f32 v[80:81], v[80:81], v[130:131]
	v_pk_mul_f32 v[78:79], v[78:79], v[128:129]
	ds_read_b128 v[162:165], v122 offset:47552
	s_nop 0
	v_mfma_f32_16x16x32_bf16 v[78:81], v[244:247], v[248:251], v[78:81]
	s_waitcnt lgkmcnt(6)
	v_pk_mul_f32 v[64:65], v[64:65], v[138:139]
	v_pk_mul_f32 v[62:63], v[62:63], v[136:137]
	s_nop 1
	v_mfma_f32_16x16x32_bf16 v[62:65], v[132:135], v[248:251], v[62:65]
	s_waitcnt lgkmcnt(4)
	v_pk_mul_f32 v[56:57], v[56:57], v[146:147]
	v_pk_mul_f32 v[54:55], v[54:55], v[144:145]
	s_nop 1
	v_mfma_f32_16x16x32_bf16 v[54:57], v[140:143], v[248:251], v[54:57]
	s_waitcnt lgkmcnt(2)
	v_pk_mul_f32 v[44:45], v[44:45], v[154:155]
	v_pk_mul_f32 v[42:43], v[42:43], v[152:153]
	s_nop 1
	v_mfma_f32_16x16x32_bf16 v[42:45], v[148:151], v[248:251], v[42:45]
	s_waitcnt lgkmcnt(0)
	v_pk_mul_f32 v[60:61], v[60:61], v[164:165]
	v_pk_mul_f32 v[58:59], v[58:59], v[162:163]
	s_nop 1
	v_mfma_f32_16x16x32_bf16 v[58:61], v[156:159], v[248:251], v[58:61]
	v_cvt_pk_bf16_f32 v101, v170, v171
	v_cvt_pk_bf16_f32 v184, v172, v173
	v_cvt_pk_bf16_f32 v185, v174, v175
	v_cvt_pk_bf16_f32 v186, v176, v177
	v_add_co_u32_e32 v166, vcc, s28, v110
	s_nop 1
	v_addc_co_u32_e32 v167, vcc, 0, v111, vcc
	v_add_co_u32_e32 v168, vcc, s30, v110
	s_nop 1
	v_addc_co_u32_e32 v169, vcc, 0, v111, vcc
	global_store_short v[166:167], v101, off offset:-4096
	global_store_short_d16_hi v[166:167], v101, off offset:-2048
	global_store_short v[166:167], v184, off
	global_store_short_d16_hi v[166:167], v184, off offset:2048
	global_store_short v[168:169], v185, off offset:-4096
	global_store_short_d16_hi v[168:169], v185, off offset:-2048
	global_store_short v[168:169], v186, off
	global_store_short_d16_hi v[168:169], v186, off offset:2048
	s_setprio 0
.LBB0_1205:
	s_min_u32 s16, s39, 56
	s_add_i32 s40, s16, 7
	s_mul_i32 s16, s40, 0x38000
	s_lshl_b32 s40, s40, 12
	s_mov_b32 s41, s17
	s_waitcnt lgkmcnt(0)
	s_barrier
	s_cmp_lg_u32 s39, 0
	s_cselect_b64 vcc, s[6:7], 0
	s_cbranch_vccnz .Lp3rx_a2
	s_waitcnt vmcnt(14)
	ds_write_b128 v99, v[18:21] offset:28160
	s_waitcnt vmcnt(13)
	ds_write_b128 v119, v[26:29] offset:36864
	s_waitcnt vmcnt(9)
	ds_write_b128 v120, v[46:49] offset:47104
	ds_write_b128 v121, v[38:41] offset:47616
	s_branch .Lp3rj_a2
.Lp3rx_a2:
	s_waitcnt vmcnt(47)
	ds_write_b128 v99, v[18:21] offset:28160
	s_waitcnt vmcnt(46)
	ds_write_b128 v119, v[26:29] offset:36864
	s_waitcnt vmcnt(45)
	ds_write_b128 v120, v[46:49] offset:47104
	s_waitcnt vmcnt(44)
	ds_write_b128 v121, v[38:41] offset:47616
.Lp3rj_a2:
	v_lshl_add_u64 v[18:19], v[102:103], 0, s[16:17]
	v_lshl_add_u64 v[26:27], v[104:105], 0, s[16:17]
	v_lshl_add_u64 v[38:39], v[108:109], 0, s[40:41]
	v_lshl_add_u64 v[40:41], v[106:107], 0, s[16:17]
	global_load_dwordx4 v[18:21], v[18:19], off
	s_nop 0
	global_load_dwordx4 v[26:29], v[26:27], off
	s_nop 0
	global_load_dwordx4 v[46:49], v[38:39], off
	s_nop 0
	s_mov_b64 exec, s[100:101]
	global_load_dwordx4 v[38:41], v[40:41], off
	s_mov_b64 exec, -1
	s_and_b64 vcc, exec, s[2:3]
	s_cbranch_vccnz .LBB0_1207
	s_setprio 2
	v_add_u32_e32 v160, 0x1000, v123
	ds_read2_b64 v[128:131], v123 offset1:4
	ds_read2_b64 v[132:135], v160 offset0:32 offset1:36
	ds_read2_b64 v[136:139], v123 offset0:8 offset1:12
	ds_read2_b64 v[140:143], v160 offset0:40 offset1:44
	ds_read2_b64 v[144:147], v123 offset0:16 offset1:20
	ds_read2_b64 v[148:151], v160 offset0:48 offset1:52
	ds_read2_b64 v[152:155], v123 offset0:24 offset1:28
	ds_read2_b64 v[156:159], v160 offset0:56 offset1:60
	ds_read_u16 v161, v124 offset:19456
	ds_read_u16 v184, v124 offset:19728
	ds_read_u16 v185, v124 offset:20000
	ds_read_u16 v186, v124 offset:20272
	ds_read_u16 v179, v124 offset:20544
	ds_read_u16 v252, v124 offset:20816
	v_cvt_pk_bf16_f32 v162, v70, v71
	v_cvt_pk_bf16_f32 v163, v72, v73
	v_cvt_pk_bf16_f32 v164, v66, v67
	v_cvt_pk_bf16_f32 v165, v68, v69
	s_waitcnt lgkmcnt(13)
	s_nop 0
	v_mfma_f32_16x16x32_bf16 v[170:173], v[128:131], v[162:165], 0
	s_waitcnt lgkmcnt(12)
	v_mfma_f32_16x16x32_bf16 v[174:177], v[132:135], v[162:165], 0
	ds_read_u16 v253, v124 offset:21088
	ds_read_u16 v208, v124 offset:21360
	ds_read_b128 v[180:183], v125 offset:8704
	v_cvt_pk_bf16_f32 v166, v74, v75
	v_cvt_pk_bf16_f32 v167, v76, v77
	v_cvt_pk_bf16_f32 v168, v78, v79
	v_cvt_pk_bf16_f32 v169, v80, v81
	s_waitcnt lgkmcnt(14)
	s_nop 0
	v_mfma_f32_16x16x32_bf16 v[170:173], v[136:139], v[166:169], v[170:173]
	s_waitcnt lgkmcnt(13)
	v_mfma_f32_16x16x32_bf16 v[174:177], v[140:143], v[166:169], v[174:177]
	ds_read_b128 v[188:191], v122 offset:18944
	ds_read_b128 v[192:195], v125 offset:9984
	v_cvt_pk_bf16_f32 v162, v62, v63
	v_cvt_pk_bf16_f32 v163, v64, v65
	v_cvt_pk_bf16_f32 v164, v54, v55
	v_cvt_pk_bf16_f32 v165, v56, v57
	s_waitcnt lgkmcnt(14)
	s_nop 0
	v_mfma_f32_16x16x32_bf16 v[170:173], v[144:147], v[162:165], v[170:173]
	s_waitcnt lgkmcnt(13)
	v_mfma_f32_16x16x32_bf16 v[174:177], v[148:151], v[162:165], v[174:177]
	ds_read_b128 v[232:235], v122 offset:19008
	ds_read_b128 v[236:239], v125 offset:11264
	v_cvt_pk_bf16_f32 v166, v42, v43
	v_cvt_pk_bf16_f32 v167, v44, v45
	v_cvt_pk_bf16_f32 v168, v58, v59
	v_cvt_pk_bf16_f32 v169, v60, v61
	s_waitcnt lgkmcnt(14)
	s_nop 0
	v_mfma_f32_16x16x32_bf16 v[170:173], v[152:155], v[166:169], v[170:173]
	s_waitcnt lgkmcnt(13)
	v_mfma_f32_16x16x32_bf16 v[174:177], v[156:159], v[166:169], v[174:177]
	ds_read_b128 v[240:243], v122 offset:19072
	ds_read_b128 v[244:247], v126 offset:8704
	s_waitcnt lgkmcnt(7)
	v_lshl_or_b32 v248, v184, 16, v161
	v_lshl_or_b32 v249, v186, 16, v185
	v_lshl_or_b32 v250, v252, 16, v179
	v_lshl_or_b32 v251, v208, 16, v253
	ds_read_b128 v[128:131], v122 offset:19136
	ds_read_b128 v[132:135], v125 offset:13824
	s_waitcnt lgkmcnt(7)
	v_pk_mul_f32 v[72:73], v[72:73], v[190:191]
	v_pk_mul_f32 v[70:71], v[70:71], v[188:189]
	ds_read_b128 v[136:139], v122 offset:19200
	ds_read_b128 v[140:143], v125 offset:15104
	v_mfma_f32_16x16x32_bf16 v[70:73], v[180:183], v[248:251], v[70:73]
	s_waitcnt lgkmcnt(7)
	v_pk_mul_f32 v[68:69], v[68:69], v[234:235]
	v_pk_mul_f32 v[66:67], v[66:67], v[232:233]
	ds_read_b128 v[144:147], v122 offset:19264
	ds_read_b128 v[148:151], v125 offset:16384
	v_mfma_f32_16x16x32_bf16 v[66:69], v[192:195], v[248:251], v[66:69]
	s_waitcnt lgkmcnt(7)
	v_pk_mul_f32 v[76:77], v[76:77], v[242:243]
	v_pk_mul_f32 v[74:75], v[74:75], v[240:241]
	ds_read_b128 v[152:155], v122 offset:19328
	ds_read_b128 v[156:159], v127 offset:8704
	v_mfma_f32_16x16x32_bf16 v[74:77], v[236:239], v[248:251], v[74:77]
	s_waitcnt lgkmcnt(7)
	v_pk_mul_f32 v[80:81], v[80:81], v[130:131]
	v_pk_mul_f32 v[78:79], v[78:79], v[128:129]
	ds_read_b128 v[162:165], v122 offset:19392
	s_nop 0
	v_mfma_f32_16x16x32_bf16 v[78:81], v[244:247], v[248:251], v[78:81]
	s_waitcnt lgkmcnt(6)
	v_pk_mul_f32 v[64:65], v[64:65], v[138:139]
	v_pk_mul_f32 v[62:63], v[62:63], v[136:137]
	s_nop 1
	v_mfma_f32_16x16x32_bf16 v[62:65], v[132:135], v[248:251], v[62:65]
	s_waitcnt lgkmcnt(4)
	v_pk_mul_f32 v[56:57], v[56:57], v[146:147]
	v_pk_mul_f32 v[54:55], v[54:55], v[144:145]
	s_nop 1
	v_mfma_f32_16x16x32_bf16 v[54:57], v[140:143], v[248:251], v[54:57]
	s_waitcnt lgkmcnt(2)
	v_pk_mul_f32 v[44:45], v[44:45], v[154:155]
	v_pk_mul_f32 v[42:43], v[42:43], v[152:153]
	s_nop 1
	v_mfma_f32_16x16x32_bf16 v[42:45], v[148:151], v[248:251], v[42:45]
	s_waitcnt lgkmcnt(0)
	v_pk_mul_f32 v[60:61], v[60:61], v[164:165]
	v_pk_mul_f32 v[58:59], v[58:59], v[162:163]
	s_nop 1
	v_mfma_f32_16x16x32_bf16 v[58:61], v[156:159], v[248:251], v[58:61]
	v_cvt_pk_bf16_f32 v209, v170, v171
	v_cvt_pk_bf16_f32 v161, v172, v173
	v_cvt_pk_bf16_f32 v184, v174, v175
	v_cvt_pk_bf16_f32 v185, v176, v177
	v_add_co_u32_e32 v166, vcc, s33, v110
	s_nop 1
	v_addc_co_u32_e32 v167, vcc, 0, v111, vcc
	v_add_co_u32_e32 v168, vcc, s35, v110
	s_nop 1
	v_addc_co_u32_e32 v169, vcc, 0, v111, vcc
	global_store_short v[166:167], v209, off offset:-4096
	global_store_short_d16_hi v[166:167], v209, off offset:-2048
	global_store_short v[166:167], v161, off
	global_store_short_d16_hi v[166:167], v161, off offset:2048
	global_store_short v[168:169], v184, off offset:-4096
	global_store_short_d16_hi v[168:169], v184, off offset:-2048
	global_store_short v[168:169], v185, off
	global_store_short_d16_hi v[168:169], v185, off offset:2048
	s_setprio 0
.LBB0_1207:
	s_min_u32 s16, s39, 55
	s_add_i32 s40, s16, 8
	s_mul_i32 s16, s40, 0x38000
	s_waitcnt lgkmcnt(0)
	s_barrier
	s_cmp_lg_u32 s39, 0
	s_cselect_b64 vcc, s[6:7], 0
	s_cbranch_vccnz .Lp3rx_a3
	ds_write_b128 v99, v[30:33]
	ds_write_b128 v119, v[34:37] offset:8704
	s_waitcnt vmcnt(12)
	ds_write_b128 v120, v[50:53] offset:18944
	ds_write_b128 v121, v[14:17] offset:19456
	s_branch .Lp3rj_a3
.Lp3rx_a3:
	s_waitcnt vmcnt(47)
	ds_write_b128 v99, v[30:33]
	s_waitcnt vmcnt(46)
	ds_write_b128 v119, v[34:37] offset:8704
	s_waitcnt vmcnt(45)
	ds_write_b128 v120, v[50:53] offset:18944
	s_waitcnt vmcnt(44)
	ds_write_b128 v121, v[14:17] offset:19456
.Lp3rj_a3:
	v_lshl_add_u64 v[14:15], v[102:103], 0, s[16:17]
	v_lshl_add_u64 v[16:17], v[104:105], 0, s[16:17]
	s_lshl_b32 s40, s40, 12
	s_mov_b32 s41, s17
	global_load_dwordx4 v[30:33], v[14:15], off
	global_load_dwordx4 v[34:37], v[16:17], off
	v_lshl_add_u64 v[14:15], v[108:109], 0, s[40:41]
	v_lshl_add_u64 v[16:17], v[106:107], 0, s[16:17]
	global_load_dwordx4 v[50:53], v[14:15], off
	s_nop 0
	s_mov_b64 exec, s[100:101]
	global_load_dwordx4 v[14:17], v[16:17], off
	s_mov_b64 exec, -1
	s_and_b64 vcc, exec, s[2:3]
	s_cbranch_vccnz .LBB0_1209
	s_setprio 2
	v_add_u32_e32 v160, 0x6800, v123
	v_add_u32_e32 v161, 0x7800, v123
	ds_read2_b64 v[128:131], v160 offset0:192 offset1:196
	ds_read2_b64 v[132:135], v161 offset0:224 offset1:228
	ds_read2_b64 v[136:139], v160 offset0:200 offset1:204
	ds_read2_b64 v[140:143], v161 offset0:232 offset1:236
	ds_read2_b64 v[144:147], v160 offset0:208 offset1:212
	ds_read2_b64 v[148:151], v161 offset0:240 offset1:244
	ds_read2_b64 v[152:155], v160 offset0:216 offset1:220
	ds_read2_b64 v[156:159], v161 offset0:248 offset1:252
	ds_read_u16 v184, v124 offset:47616
	ds_read_u16 v185, v124 offset:47888
	ds_read_u16 v186, v124 offset:48160
	ds_read_u16 v179, v124 offset:48432
	ds_read_u16 v252, v124 offset:48704
	ds_read_u16 v253, v124 offset:48976
	v_cvt_pk_bf16_f32 v162, v70, v71
	v_cvt_pk_bf16_f32 v163, v72, v73
	v_cvt_pk_bf16_f32 v164, v66, v67
	v_cvt_pk_bf16_f32 v165, v68, v69
	s_waitcnt lgkmcnt(13)
	s_nop 0
	v_mfma_f32_16x16x32_bf16 v[170:173], v[128:131], v[162:165], 0
	s_waitcnt lgkmcnt(12)
	v_mfma_f32_16x16x32_bf16 v[174:177], v[132:135], v[162:165], 0
	ds_read_u16 v208, v124 offset:49248
	ds_read_u16 v209, v124 offset:49520
	ds_read_b128 v[180:183], v125 offset:36864
	v_cvt_pk_bf16_f32 v166, v74, v75
	v_cvt_pk_bf16_f32 v167, v76, v77
	v_cvt_pk_bf16_f32 v168, v78, v79
	v_cvt_pk_bf16_f32 v169, v80, v81
	s_waitcnt lgkmcnt(14)
	s_nop 0
	v_mfma_f32_16x16x32_bf16 v[170:173], v[136:139], v[166:169], v[170:173]
	s_waitcnt lgkmcnt(13)
	v_mfma_f32_16x16x32_bf16 v[174:177], v[140:143], v[166:169], v[174:177]
	ds_read_b128 v[188:191], v122 offset:47104
	ds_read_b128 v[192:195], v125 offset:38144
	v_cvt_pk_bf16_f32 v162, v62, v63
	v_cvt_pk_bf16_f32 v163, v64, v65
	v_cvt_pk_bf16_f32 v164, v54, v55
	v_cvt_pk_bf16_f32 v165, v56, v57
	s_waitcnt lgkmcnt(14)
	s_nop 0
	v_mfma_f32_16x16x32_bf16 v[170:173], v[144:147], v[162:165], v[170:173]
	s_waitcnt lgkmcnt(13)
	v_mfma_f32_16x16x32_bf16 v[174:177], v[148:151], v[162:165], v[174:177]
	ds_read_b128 v[232:235], v122 offset:47168
	ds_read_b128 v[236:239], v125 offset:39424
	v_cvt_pk_bf16_f32 v166, v42, v43
	v_cvt_pk_bf16_f32 v167, v44, v45
	v_cvt_pk_bf16_f32 v168, v58, v59
	v_cvt_pk_bf16_f32 v169, v60, v61
	s_waitcnt lgkmcnt(14)
	s_nop 0
	v_mfma_f32_16x16x32_bf16 v[170:173], v[152:155], v[166:169], v[170:173]
	s_waitcnt lgkmcnt(13)
	v_mfma_f32_16x16x32_bf16 v[174:177], v[156:159], v[166:169], v[174:177]
	ds_read_b128 v[240:243], v122 offset:47232
	ds_read_b128 v[244:247], v126 offset:36864
	s_waitcnt lgkmcnt(7)
	v_lshl_or_b32 v248, v185, 16, v184
	v_lshl_or_b32 v249, v179, 16, v186
	v_lshl_or_b32 v250, v253, 16, v252
	v_lshl_or_b32 v251, v209, 16, v208
	ds_read_b128 v[128:131], v122 offset:47296
	ds_read_b128 v[132:135], v125 offset:41984
	s_waitcnt lgkmcnt(7)
	v_pk_mul_f32 v[72:73], v[72:73], v[190:191]
	v_pk_mul_f32 v[70:71], v[70:71], v[188:189]
	ds_read_b128 v[136:139], v122 offset:47360
	ds_read_b128 v[140:143], v125 offset:43264
	v_mfma_f32_16x16x32_bf16 v[70:73], v[180:183], v[248:251], v[70:73]
	s_waitcnt lgkmcnt(7)
	v_pk_mul_f32 v[68:69], v[68:69], v[234:235]
	v_pk_mul_f32 v[66:67], v[66:67], v[232:233]
	ds_read_b128 v[144:147], v122 offset:47424
	ds_read_b128 v[148:151], v125 offset:44544
	v_mfma_f32_16x16x32_bf16 v[66:69], v[192:195], v[248:251], v[66:69]
	s_waitcnt lgkmcnt(7)
	v_pk_mul_f32 v[76:77], v[76:77], v[242:243]
	v_pk_mul_f32 v[74:75], v[74:75], v[240:241]
	ds_read_b128 v[152:155], v122 offset:47488
	ds_read_b128 v[156:159], v127 offset:36864
	v_mfma_f32_16x16x32_bf16 v[74:77], v[236:239], v[248:251], v[74:77]
	s_waitcnt lgkmcnt(7)
	v_pk_mul_f32 v[80:81], v[80:81], v[130:131]
	v_pk_mul_f32 v[78:79], v[78:79], v[128:129]
	ds_read_b128 v[162:165], v122 offset:47552
	s_nop 0
	v_mfma_f32_16x16x32_bf16 v[78:81], v[244:247], v[248:251], v[78:81]
	s_waitcnt lgkmcnt(6)
	v_pk_mul_f32 v[64:65], v[64:65], v[138:139]
	v_pk_mul_f32 v[62:63], v[62:63], v[136:137]
	s_nop 1
	v_mfma_f32_16x16x32_bf16 v[62:65], v[132:135], v[248:251], v[62:65]
	s_waitcnt lgkmcnt(4)
	v_pk_mul_f32 v[56:57], v[56:57], v[146:147]
	v_pk_mul_f32 v[54:55], v[54:55], v[144:145]
	s_nop 1
	v_mfma_f32_16x16x32_bf16 v[54:57], v[140:143], v[248:251], v[54:57]
	s_waitcnt lgkmcnt(2)
	v_pk_mul_f32 v[44:45], v[44:45], v[154:155]
	v_pk_mul_f32 v[42:43], v[42:43], v[152:153]
	s_nop 1
	v_mfma_f32_16x16x32_bf16 v[42:45], v[148:151], v[248:251], v[42:45]
	s_waitcnt lgkmcnt(0)
	v_pk_mul_f32 v[60:61], v[60:61], v[164:165]
	v_pk_mul_f32 v[58:59], v[58:59], v[162:163]
	s_nop 1
	v_mfma_f32_16x16x32_bf16 v[58:61], v[156:159], v[248:251], v[58:61]
	v_cvt_pk_bf16_f32 v101, v170, v171
	v_cvt_pk_bf16_f32 v184, v172, v173
	v_cvt_pk_bf16_f32 v185, v174, v175
	v_cvt_pk_bf16_f32 v186, v176, v177
	v_add_co_u32_e32 v166, vcc, s37, v110
	s_nop 1
	v_addc_co_u32_e32 v167, vcc, 0, v111, vcc
	v_add_co_u32_e32 v168, vcc, s38, v110
	s_nop 1
	v_addc_co_u32_e32 v169, vcc, 0, v111, vcc
	global_store_short v[166:167], v101, off offset:-4096
	global_store_short_d16_hi v[166:167], v101, off offset:-2048
	global_store_short v[166:167], v184, off
	global_store_short_d16_hi v[166:167], v184, off offset:2048
	global_store_short v[168:169], v185, off offset:-4096
	global_store_short_d16_hi v[168:169], v185, off offset:-2048
	global_store_short v[168:169], v186, off
	global_store_short_d16_hi v[168:169], v186, off offset:2048
	s_setprio 0
.LBB0_1209:
	s_waitcnt lgkmcnt(0)
	s_barrier
	s_add_i32 s16, s39, 4
	v_lshl_add_u64 v[110:111], v[110:111], 0, s[18:19]
	s_cmp_lg_u32 s39, 0
	s_cselect_b64 vcc, s[6:7], 0
	s_cbranch_vccnz .Lp3rx_a4
	s_waitcnt vmcnt(15)
	ds_write_b128 v99, v[82:85] offset:28160
	s_waitcnt vmcnt(14)
	ds_write_b128 v119, v[86:89] offset:36864
	s_waitcnt vmcnt(13)
	ds_write_b128 v120, v[90:93] offset:47104
	s_waitcnt vmcnt(12)
	ds_write_b128 v121, v[94:97] offset:47616
	s_branch .Lp3rj_a4
.Lp3rx_a4:
	s_waitcnt vmcnt(47)
	ds_write_b128 v99, v[82:85] offset:28160
	s_waitcnt vmcnt(46)
	ds_write_b128 v119, v[86:89] offset:36864
	s_waitcnt vmcnt(45)
	ds_write_b128 v120, v[90:93] offset:47104
	s_waitcnt vmcnt(44)
	ds_write_b128 v121, v[94:97] offset:47616
.Lp3rj_a4:
	s_cmp_lt_u32 s39, 60
	s_cbranch_scc0 .LBB0_1211
	s_mov_b32 s39, s16
	s_branch .LBB0_1201

.LBB0_1218:
	s_min_u32 s8, s28, 57
	s_add_i32 s29, s8, 6
	s_mul_i32 s8, s29, 0x38000
	s_lshl_b32 s30, s29, 12
	s_mov_b32 s31, s9
	s_waitcnt lgkmcnt(0)
	s_barrier
	s_cmp_lg_u32 s28, 0
	s_cselect_b64 vcc, s[6:7], 0
	s_cbranch_vccnz .Lp3rx_b1
	s_waitcnt vmcnt(15)
	ds_write_b128 v92, v[6:9]
	s_waitcnt vmcnt(14)
	ds_write_b128 v93, v[10:13] offset:8704
	s_waitcnt vmcnt(13)
	ds_write_b128 v94, v[14:17] offset:18944
	s_waitcnt vmcnt(12)
	ds_write_b128 v95, v[22:25] offset:19456
	s_branch .Lp3rj_b1
.Lp3rx_b1:
	s_waitcnt vmcnt(47)
	ds_write_b128 v92, v[6:9]
	s_waitcnt vmcnt(46)
	ds_write_b128 v93, v[10:13] offset:8704
	s_waitcnt vmcnt(45)
	ds_write_b128 v94, v[14:17] offset:18944
	s_waitcnt vmcnt(44)
	ds_write_b128 v95, v[22:25] offset:19456
.Lp3rj_b1:
	v_lshl_add_u64 v[6:7], v[82:83], 0, s[8:9]
	v_lshl_add_u64 v[10:11], v[84:85], 0, s[8:9]
	v_lshl_add_u64 v[14:15], v[86:87], 0, s[30:31]
	v_lshl_add_u64 v[22:23], v[88:89], 0, s[8:9]
	global_load_dwordx4 v[6:9], v[6:7], off
	s_nop 0
	global_load_dwordx4 v[10:13], v[10:11], off
	s_nop 0
	global_load_dwordx4 v[14:17], v[14:15], off
	s_nop 0
	s_mov_b64 exec, s[100:101]
	global_load_dwordx4 v[22:25], v[22:23], off offset:1024
	s_mov_b64 exec, -1
	s_and_b64 vcc, exec, s[2:3]
	v_add_u32_e32 v103, 0x6800, v97
	v_add_u32_e32 v102, 0x7000, v97
	s_cbranch_vccnz .LBB0_1220
	s_setprio 2
	ds_read2_b64 v[106:109], v103 offset0:192 offset1:196
	ds_read2_b64 v[118:121], v102 offset0:224 offset1:228
	ds_read2_b64 v[122:125], v103 offset0:200 offset1:204
	v_cvt_pk_bf16_f32 v114, v2, v3
	v_cvt_pk_bf16_f32 v115, v4, v5
	v_cvt_pk_bf16_f32 v116, v62, v63
	v_cvt_pk_bf16_f32 v117, v64, v65
	v_cvt_pk_bf16_f32 v126, v54, v55
	v_cvt_pk_bf16_f32 v127, v56, v57
	s_waitcnt lgkmcnt(2)
	v_mfma_f32_16x16x32_bf16 v[106:109], v[106:109], v[114:117], 0
	v_cvt_pk_bf16_f32 v128, v58, v59
	v_cvt_pk_bf16_f32 v129, v60, v61
	s_waitcnt lgkmcnt(1)
	v_mfma_f32_16x16x32_bf16 v[114:117], v[118:121], v[114:117], 0
	s_waitcnt lgkmcnt(0)
	v_mfma_f32_16x16x32_bf16 v[106:109], v[122:125], v[126:129], v[106:109]
	ds_read2_b64 v[118:121], v102 offset0:232 offset1:236
	ds_read_u16 v105, v99 offset:47616
	ds_read_u16 v110, v99 offset:48704
	ds_read_u16 v111, v99 offset:48976
	ds_read_u16 v113, v99 offset:49248
	ds_read_u16 v122, v99 offset:49520
	ds_read_u16 v130, v99 offset:47888
	ds_read_u16 v131, v99 offset:48160
	ds_read_u16 v132, v99 offset:48432
	s_waitcnt lgkmcnt(8)
	v_mfma_f32_16x16x32_bf16 v[114:117], v[118:121], v[126:129], v[114:117]
	s_waitcnt lgkmcnt(3)
	v_perm_b32 v121, v122, v113, s14
	ds_read_b128 v[122:125], v100 offset:36864
	ds_read_b128 v[126:129], v96 offset:47104
	s_waitcnt lgkmcnt(2)
	v_perm_b32 v119, v132, v131, s14
	v_perm_b32 v118, v130, v105, s14
	ds_read_b128 v[130:133], v100 offset:38144
	ds_read_b128 v[134:137], v96 offset:47168
	v_perm_b32 v120, v111, v110, s14
	s_waitcnt lgkmcnt(2)
	v_pk_mul_f32 v[4:5], v[4:5], v[128:129]
	v_pk_mul_f32 v[2:3], v[2:3], v[126:127]
	ds_read_b128 v[126:129], v96 offset:47232
	s_waitcnt lgkmcnt(1)
	v_pk_mul_f32 v[64:65], v[64:65], v[136:137]
	v_mfma_f32_16x16x32_bf16 v[2:5], v[122:125], v[118:121], v[2:5]
	ds_read_b128 v[122:125], v100 offset:39424
	v_pk_mul_f32 v[62:63], v[62:63], v[134:135]
	ds_read_b128 v[134:137], v101 offset:36864
	v_cvt_pk_bf16_f32 v105, v106, v107
	v_mfma_f32_16x16x32_bf16 v[62:65], v[130:133], v[118:121], v[62:65]
	ds_read_b128 v[130:133], v96 offset:47296
	v_add_co_u32_e32 v106, vcc, s17, v90
	s_waitcnt lgkmcnt(3)
	v_pk_mul_f32 v[56:57], v[56:57], v[128:129]
	v_addc_co_u32_e32 v107, vcc, 0, v91, vcc
	v_add_co_u32_e32 v110, vcc, s18, v90
	v_pk_mul_f32 v[54:55], v[54:55], v[126:127]
	s_nop 0
	v_addc_co_u32_e32 v111, vcc, 0, v91, vcc
	s_waitcnt lgkmcnt(0)
	v_pk_mul_f32 v[60:61], v[60:61], v[132:133]
	v_pk_mul_f32 v[58:59], v[58:59], v[130:131]
	global_store_short v[110:111], v105, off offset:-4096
	global_store_short_d16_hi v[106:107], v105, off offset:2048
	v_add_co_u32_e32 v106, vcc, s19, v90
	v_mfma_f32_16x16x32_bf16 v[54:57], v[122:125], v[118:121], v[54:57]
	s_nop 0
	v_addc_co_u32_e32 v107, vcc, 0, v91, vcc
	v_cvt_pk_bf16_f32 v105, v108, v109
	v_mfma_f32_16x16x32_bf16 v[58:61], v[134:137], v[118:121], v[58:61]
	v_add_co_u32_e32 v108, vcc, s20, v90
	global_store_short v[110:111], v105, off
	global_store_short_d16_hi v[110:111], v105, off offset:2048
	v_cvt_pk_bf16_f32 v105, v114, v115
	v_addc_co_u32_e32 v109, vcc, 0, v91, vcc
	global_store_short v[108:109], v105, off offset:-4096
	global_store_short_d16_hi v[106:107], v105, off offset:2048
	v_cvt_pk_bf16_f32 v105, v116, v117
	global_store_short v[108:109], v105, off
	global_store_short_d16_hi v[108:109], v105, off offset:2048
	s_setprio 0
.LBB0_1220:
	s_min_u32 s8, s28, 56
	s_add_i32 s29, s8, 7
	s_mul_i32 s8, s29, 0x38000
	s_lshl_b32 s30, s29, 12
	s_mov_b32 s31, s9
	s_waitcnt lgkmcnt(0)
	s_barrier
	s_cmp_lg_u32 s28, 0
	s_cselect_b64 vcc, s[6:7], 0
	s_cbranch_vccnz .Lp3rx_b2
	s_waitcnt vmcnt(15)
	ds_write_b128 v92, v[18:21] offset:28160
	s_waitcnt vmcnt(14)
	ds_write_b128 v93, v[26:29] offset:36864
	s_waitcnt vmcnt(10)
	ds_write_b128 v94, v[42:45] offset:47104
	ds_write_b128 v95, v[30:33] offset:47616
	s_branch .Lp3rj_b2
.Lp3rx_b2:
	s_waitcnt vmcnt(47)
	ds_write_b128 v92, v[18:21] offset:28160
	s_waitcnt vmcnt(46)
	ds_write_b128 v93, v[26:29] offset:36864
	s_waitcnt vmcnt(45)
	ds_write_b128 v94, v[42:45] offset:47104
	s_waitcnt vmcnt(44)
	ds_write_b128 v95, v[30:33] offset:47616
.Lp3rj_b2:
	v_lshl_add_u64 v[18:19], v[82:83], 0, s[8:9]
	v_lshl_add_u64 v[26:27], v[84:85], 0, s[8:9]
	v_lshl_add_u64 v[30:31], v[86:87], 0, s[30:31]
	v_lshl_add_u64 v[32:33], v[88:89], 0, s[8:9]
	global_load_dwordx4 v[18:21], v[18:19], off
	s_nop 0
	global_load_dwordx4 v[26:29], v[26:27], off
	s_nop 0
	global_load_dwordx4 v[42:45], v[30:31], off
	s_nop 0
	s_mov_b64 exec, s[100:101]
	global_load_dwordx4 v[30:33], v[32:33], off offset:1024
	s_mov_b64 exec, -1
	s_and_b64 vcc, exec, s[2:3]
	s_cbranch_vccnz .LBB0_1222
	s_setprio 2
	ds_read2_b64 v[106:109], v97 offset1:4
	ds_read2_b64 v[118:121], v104 offset0:32 offset1:36
	ds_read2_b64 v[122:125], v97 offset0:8 offset1:12
	v_cvt_pk_bf16_f32 v114, v2, v3
	v_cvt_pk_bf16_f32 v115, v4, v5
	v_cvt_pk_bf16_f32 v116, v62, v63
	v_cvt_pk_bf16_f32 v117, v64, v65
	v_cvt_pk_bf16_f32 v126, v54, v55
	v_cvt_pk_bf16_f32 v127, v56, v57
	s_waitcnt lgkmcnt(2)
	v_mfma_f32_16x16x32_bf16 v[106:109], v[106:109], v[114:117], 0
	v_cvt_pk_bf16_f32 v128, v58, v59
	v_cvt_pk_bf16_f32 v129, v60, v61
	s_waitcnt lgkmcnt(1)
	v_mfma_f32_16x16x32_bf16 v[114:117], v[118:121], v[114:117], 0
	ds_read2_b64 v[118:121], v104 offset0:40 offset1:44
	ds_read_u16 v104, v99 offset:19456
	ds_read_u16 v105, v99 offset:20544
	ds_read_u16 v110, v99 offset:20816
	ds_read_u16 v111, v99 offset:21088
	ds_read_u16 v113, v99 offset:21360
	ds_read_u16 v130, v99 offset:19728
	ds_read_u16 v131, v99 offset:20000
	ds_read_u16 v132, v99 offset:20272
	s_waitcnt lgkmcnt(9)
	v_mfma_f32_16x16x32_bf16 v[106:109], v[122:125], v[126:129], v[106:109]
	ds_read_b128 v[122:125], v100 offset:8704
	s_waitcnt lgkmcnt(9)
	v_mfma_f32_16x16x32_bf16 v[114:117], v[118:121], v[126:129], v[114:117]
	ds_read_b128 v[126:129], v96 offset:18944
	s_waitcnt lgkmcnt(2)
	v_perm_b32 v119, v132, v131, s14
	v_perm_b32 v118, v130, v104, s14
	ds_read_b128 v[130:133], v100 offset:9984
	ds_read_b128 v[134:137], v96 offset:19008
	v_perm_b32 v121, v113, v111, s14
	v_perm_b32 v120, v110, v105, s14
	s_waitcnt lgkmcnt(2)
	v_pk_mul_f32 v[4:5], v[4:5], v[128:129]
	v_pk_mul_f32 v[2:3], v[2:3], v[126:127]
	s_waitcnt lgkmcnt(0)
	v_pk_mul_f32 v[64:65], v[64:65], v[136:137]
	v_pk_mul_f32 v[62:63], v[62:63], v[134:135]
	v_mfma_f32_16x16x32_bf16 v[2:5], v[122:125], v[118:121], v[2:5]
	ds_read_b128 v[122:125], v100 offset:11264
	ds_read_b128 v[134:137], v101 offset:8704
	ds_read_b128 v[126:129], v96 offset:19072
	v_mfma_f32_16x16x32_bf16 v[62:65], v[130:133], v[118:121], v[62:65]
	ds_read_b128 v[130:133], v96 offset:19136
	v_add_co_u32_e32 v104, vcc, s21, v90
	v_cvt_pk_bf16_f32 v110, v106, v107
	s_nop 0
	v_addc_co_u32_e32 v105, vcc, 0, v91, vcc
	v_add_co_u32_e32 v106, vcc, s22, v90
	s_waitcnt lgkmcnt(1)
	v_pk_mul_f32 v[56:57], v[56:57], v[128:129]
	v_addc_co_u32_e32 v107, vcc, 0, v91, vcc
	global_store_short v[106:107], v110, off offset:-4096
	global_store_short_d16_hi v[104:105], v110, off offset:2048
	v_cvt_pk_bf16_f32 v104, v108, v109
	v_pk_mul_f32 v[54:55], v[54:55], v[126:127]
	s_waitcnt lgkmcnt(0)
	v_pk_mul_f32 v[60:61], v[60:61], v[132:133]
	v_pk_mul_f32 v[58:59], v[58:59], v[130:131]
	global_store_short v[106:107], v104, off
	global_store_short_d16_hi v[106:107], v104, off offset:2048
	v_add_co_u32_e32 v104, vcc, s23, v90
	v_mfma_f32_16x16x32_bf16 v[54:57], v[122:125], v[118:121], v[54:57]
	s_nop 0
	v_addc_co_u32_e32 v105, vcc, 0, v91, vcc
	v_add_co_u32_e32 v106, vcc, s24, v90
	v_mfma_f32_16x16x32_bf16 v[58:61], v[134:137], v[118:121], v[58:61]
	v_cvt_pk_bf16_f32 v108, v114, v115
	v_addc_co_u32_e32 v107, vcc, 0, v91, vcc
	global_store_short v[106:107], v108, off offset:-4096
	global_store_short_d16_hi v[104:105], v108, off offset:2048
	v_cvt_pk_bf16_f32 v104, v116, v117
	global_store_short v[106:107], v104, off
	global_store_short_d16_hi v[106:107], v104, off offset:2048
	s_setprio 0
.LBB0_1222:
	s_min_u32 s8, s28, 55
	s_add_i32 s29, s8, 8
	s_mul_i32 s8, s29, 0x38000
	s_lshl_b32 s30, s29, 12
	s_mov_b32 s31, s9
	s_waitcnt lgkmcnt(0)
	s_barrier
	s_cmp_lg_u32 s28, 0
	s_cselect_b64 vcc, s[6:7], 0
	s_cbranch_vccnz .Lp3rx_b3
	ds_write_b128 v92, v[34:37]
	ds_write_b128 v93, v[38:41] offset:8704
	s_waitcnt vmcnt(13)
	ds_write_b128 v94, v[46:49] offset:18944
	s_waitcnt vmcnt(12)
	ds_write_b128 v95, v[50:53] offset:19456
	s_branch .Lp3rj_b3
.Lp3rx_b3:
	s_waitcnt vmcnt(47)
	ds_write_b128 v92, v[34:37]
	s_waitcnt vmcnt(46)
	ds_write_b128 v93, v[38:41] offset:8704
	s_waitcnt vmcnt(45)
	ds_write_b128 v94, v[46:49] offset:18944
	s_waitcnt vmcnt(44)
	ds_write_b128 v95, v[50:53] offset:19456
.Lp3rj_b3:
	v_lshl_add_u64 v[34:35], v[82:83], 0, s[8:9]
	v_lshl_add_u64 v[38:39], v[84:85], 0, s[8:9]
	v_lshl_add_u64 v[46:47], v[86:87], 0, s[30:31]
	v_lshl_add_u64 v[50:51], v[88:89], 0, s[8:9]
	global_load_dwordx4 v[34:37], v[34:35], off
	s_nop 0
	global_load_dwordx4 v[38:41], v[38:39], off
	s_nop 0
	global_load_dwordx4 v[46:49], v[46:47], off
	s_nop 0
	s_mov_b64 exec, s[100:101]
	global_load_dwordx4 v[50:53], v[50:51], off offset:1024
	s_mov_b64 exec, -1
	s_and_b64 vcc, exec, s[2:3]
	s_cbranch_vccnz .LBB0_1224
	s_setprio 2
	ds_read2_b64 v[104:107], v103 offset0:192 offset1:196
	ds_read2_b64 v[114:117], v102 offset0:224 offset1:228
	ds_read2_b64 v[118:121], v103 offset0:200 offset1:204
	v_cvt_pk_bf16_f32 v108, v2, v3
	v_cvt_pk_bf16_f32 v109, v4, v5
	v_cvt_pk_bf16_f32 v110, v62, v63
	v_cvt_pk_bf16_f32 v111, v64, v65
	v_cvt_pk_bf16_f32 v122, v54, v55
	v_cvt_pk_bf16_f32 v123, v56, v57
	s_waitcnt lgkmcnt(2)
	v_mfma_f32_16x16x32_bf16 v[104:107], v[104:107], v[108:111], 0
	v_cvt_pk_bf16_f32 v124, v58, v59
	v_cvt_pk_bf16_f32 v125, v60, v61
	s_waitcnt lgkmcnt(1)
	v_mfma_f32_16x16x32_bf16 v[108:111], v[114:117], v[108:111], 0
	s_waitcnt lgkmcnt(0)
	v_mfma_f32_16x16x32_bf16 v[104:107], v[118:121], v[122:125], v[104:107]
	ds_read2_b64 v[114:117], v102 offset0:232 offset1:236
	ds_read_u16 v102, v99 offset:47616
	ds_read_u16 v103, v99 offset:48704
	ds_read_u16 v113, v99 offset:48976
	ds_read_u16 v118, v99 offset:49248
	ds_read_u16 v119, v99 offset:49520
	ds_read_u16 v126, v99 offset:47888
	ds_read_u16 v127, v99 offset:48160
	ds_read_u16 v128, v99 offset:48432
	s_waitcnt lgkmcnt(8)
	v_mfma_f32_16x16x32_bf16 v[108:111], v[114:117], v[122:125], v[108:111]
	s_waitcnt lgkmcnt(3)
	v_perm_b32 v117, v119, v118, s14
	ds_read_b128 v[118:121], v100 offset:36864
	ds_read_b128 v[122:125], v96 offset:47104
	s_waitcnt lgkmcnt(2)
	v_perm_b32 v115, v128, v127, s14
	v_perm_b32 v114, v126, v102, s14
	ds_read_b128 v[126:129], v100 offset:38144
	ds_read_b128 v[130:133], v96 offset:47168
	v_perm_b32 v116, v113, v103, s14
	s_waitcnt lgkmcnt(2)
	v_pk_mul_f32 v[4:5], v[4:5], v[124:125]
	v_pk_mul_f32 v[2:3], v[2:3], v[122:123]
	ds_read_b128 v[122:125], v96 offset:47232
	s_waitcnt lgkmcnt(1)
	v_pk_mul_f32 v[64:65], v[64:65], v[132:133]
	v_mfma_f32_16x16x32_bf16 v[2:5], v[118:121], v[114:117], v[2:5]
	ds_read_b128 v[118:121], v100 offset:39424
	v_pk_mul_f32 v[62:63], v[62:63], v[130:131]
	ds_read_b128 v[130:133], v101 offset:36864
	v_add_co_u32_e32 v102, vcc, s25, v90
	v_mfma_f32_16x16x32_bf16 v[62:65], v[126:129], v[114:117], v[62:65]
	ds_read_b128 v[126:129], v96 offset:47296
	v_addc_co_u32_e32 v103, vcc, 0, v91, vcc
	v_cvt_pk_bf16_f32 v113, v104, v105
	v_add_co_u32_e32 v104, vcc, s26, v90
	s_waitcnt lgkmcnt(3)
	v_pk_mul_f32 v[56:57], v[56:57], v[124:125]
	v_addc_co_u32_e32 v105, vcc, 0, v91, vcc
	global_store_short v[104:105], v113, off offset:-4096
	global_store_short_d16_hi v[102:103], v113, off offset:2048
	v_cvt_pk_bf16_f32 v102, v106, v107
	v_pk_mul_f32 v[54:55], v[54:55], v[122:123]
	s_waitcnt lgkmcnt(0)
	v_pk_mul_f32 v[60:61], v[60:61], v[128:129]
	v_pk_mul_f32 v[58:59], v[58:59], v[126:127]
	global_store_short v[104:105], v102, off
	global_store_short_d16_hi v[104:105], v102, off offset:2048
	v_add_co_u32_e32 v102, vcc, s12, v90
	v_mfma_f32_16x16x32_bf16 v[54:57], v[118:121], v[114:117], v[54:57]
	s_nop 0
	v_addc_co_u32_e32 v103, vcc, 0, v91, vcc
	v_add_co_u32_e32 v104, vcc, s27, v90
	v_mfma_f32_16x16x32_bf16 v[58:61], v[130:133], v[114:117], v[58:61]
	v_cvt_pk_bf16_f32 v106, v108, v109
	v_addc_co_u32_e32 v105, vcc, 0, v91, vcc
	global_store_short v[104:105], v106, off offset:-4096
	global_store_short_d16_hi v[102:103], v106, off offset:2048
	v_cvt_pk_bf16_f32 v102, v110, v111
	global_store_short v[104:105], v102, off
	global_store_short_d16_hi v[104:105], v102, off offset:2048
	s_setprio 0
.LBB0_1224:
	s_waitcnt lgkmcnt(0)
	s_barrier
	s_add_i32 s8, s28, 4
	v_lshl_add_u64 v[90:91], v[90:91], 0, s[10:11]
	s_cmp_lg_u32 s28, 0
	s_cselect_b64 vcc, s[6:7], 0
	s_cbranch_vccnz .Lp3rx_b4
	s_waitcnt vmcnt(15)
	ds_write_b128 v92, v[66:69] offset:28160
	s_waitcnt vmcnt(14)
	ds_write_b128 v93, v[70:73] offset:36864
	s_waitcnt vmcnt(13)
	ds_write_b128 v94, v[74:77] offset:47104
	s_waitcnt vmcnt(12)
	ds_write_b128 v95, v[78:81] offset:47616
	s_branch .Lp3rj_b4
.Lp3rx_b4:
	s_waitcnt vmcnt(47)
	ds_write_b128 v92, v[66:69] offset:28160
	s_waitcnt vmcnt(46)
	ds_write_b128 v93, v[70:73] offset:36864
	s_waitcnt vmcnt(45)
	ds_write_b128 v94, v[74:77] offset:47104
	s_waitcnt vmcnt(44)
	ds_write_b128 v95, v[78:81] offset:47616
.Lp3rj_b4:
	s_cmp_lt_u32 s28, 60
	s_cbranch_scc0 .LBB0_1226
	s_mov_b32 s28, s8
	s_branch .LBB0_1216
